# combo13 + K-loop heads aligned to 64 B (loop-head instruction-fetch alignment)
# baseline (speedup 1.0000x reference)
; template <class Epi, class Sched = StaticOrder>
; DI void gemm_phase(LAS unsigned char* lds, const Gemm g, const Sched& S, const Epi& E) {
;     ...
;     const bool has_next = S.next(ui + 1, nxt);
;     const char* nA = has_next ? (const char*)g.A + (size_t)nxt.pm * tstep : cA; const char* nB = has_next ? (const char*)g.Bt + (size_t)nxt.pn * tstep : cB;
;     ...
; #pragma unroll
;     for (int a = 0; a < 2; ++a)
; #pragma unroll
;       for (int b = 0; b < 2; ++b)
; #pragma unroll
;         for (int m = 0; m < 4; ++m)
; #pragma unroll
;           for (int n = 0; n < 2; ++n) acc[a][b][m][n] = (f32x4){0.f, 0.f, 0.f, 0.f};
;     cur = nxt; cA = nA; cB = nB; ++ui;
.LBB0_345:
	s_ashr_i32 s31, s30, 31
	v_cmp_lt_i64_e32 vcc, s[10:11], v[150:151]
	s_lshl_b64 s[10:11], s[30:31], 20
	s_add_u32 s34, s33, s10
	s_addc_u32 s35, s38, s11
	s_and_b64 s[10:11], vcc, exec
	s_cselect_b32 s31, s35, s7
	s_cselect_b32 s42, s34, s6
	s_ashr_i32 s29, s28, 31
	s_lshl_b64 s[10:11], s[28:29], 20
	s_add_u32 s36, s39, s10
	s_addc_u32 s37, s40, s11
	s_and_b64 s[10:11], vcc, exec
	s_cselect_b32 s29, s37, s9
	s_cselect_b32 s43, s36, s8
	s_add_u32 s6, s6, 0x80080
	s_addc_u32 s7, s7, 0
	s_add_u32 s44, s8, 0x100
	v_mov_b32_e32 v0, 0
	s_addc_u32 s45, s9, 0
	s_mov_b32 s52, -2
	v_mov_b32_e32 v1, v0
	v_mov_b32_e32 v2, v0
	v_mov_b32_e32 v3, v0
	v_mov_b32_e32 v4, v0
	v_mov_b32_e32 v5, v0
	v_mov_b32_e32 v6, v0
	v_mov_b32_e32 v7, v0
	v_mov_b32_e32 v8, v0
	v_mov_b32_e32 v9, v0
	v_mov_b32_e32 v10, v0
	v_mov_b32_e32 v11, v0
	v_mov_b32_e32 v16, v0
	v_mov_b32_e32 v17, v0
	v_mov_b32_e32 v18, v0
	v_mov_b32_e32 v19, v0
	v_mov_b32_e32 v24, v0
	v_mov_b32_e32 v25, v0
	v_mov_b32_e32 v26, v0
	v_mov_b32_e32 v27, v0
	v_mov_b32_e32 v32, v0
	v_mov_b32_e32 v33, v0
	v_mov_b32_e32 v34, v0
	v_mov_b32_e32 v35, v0
	v_mov_b32_e32 v40, v0
	v_mov_b32_e32 v41, v0
	v_mov_b32_e32 v42, v0
	v_mov_b32_e32 v43, v0
	v_mov_b32_e32 v48, v0
	v_mov_b32_e32 v49, v0
	v_mov_b32_e32 v50, v0
	v_mov_b32_e32 v51, v0
	v_mov_b32_e32 v12, v0
	v_mov_b32_e32 v13, v0
	v_mov_b32_e32 v14, v0
	v_mov_b32_e32 v15, v0
	v_mov_b32_e32 v20, v0
	v_mov_b32_e32 v21, v0
	v_mov_b32_e32 v22, v0
	v_mov_b32_e32 v23, v0
	v_mov_b32_e32 v28, v0
	v_mov_b32_e32 v29, v0
	v_mov_b32_e32 v30, v0
	v_mov_b32_e32 v31, v0
	v_mov_b32_e32 v36, v0
	v_mov_b32_e32 v37, v0
	v_mov_b32_e32 v38, v0
	v_mov_b32_e32 v39, v0
	v_mov_b32_e32 v44, v0
	v_mov_b32_e32 v45, v0
	v_mov_b32_e32 v46, v0
	v_mov_b32_e32 v47, v0
	v_mov_b32_e32 v52, v0
	v_mov_b32_e32 v53, v0
	v_mov_b32_e32 v54, v0
	v_mov_b32_e32 v55, v0
	v_mov_b32_e32 v56, v0
	v_mov_b32_e32 v57, v0
	v_mov_b32_e32 v58, v0
	v_mov_b32_e32 v59, v0
	v_mov_b32_e32 v60, v0
	v_mov_b32_e32 v61, v0
	v_mov_b32_e32 v62, v0
	v_mov_b32_e32 v63, v0
	v_mov_b32_e32 v64, v0
	v_mov_b32_e32 v65, v0
	v_mov_b32_e32 v66, v0
	v_mov_b32_e32 v67, v0
	v_mov_b32_e32 v68, v0
	v_mov_b32_e32 v69, v0
	v_mov_b32_e32 v70, v0
	v_mov_b32_e32 v71, v0
	v_mov_b32_e32 v72, v0
	v_mov_b32_e32 v73, v0
	v_mov_b32_e32 v74, v0
	v_mov_b32_e32 v75, v0
	v_mov_b32_e32 v80, v0
	v_mov_b32_e32 v81, v0
	v_mov_b32_e32 v82, v0
	v_mov_b32_e32 v83, v0
	v_mov_b32_e32 v88, v0
	v_mov_b32_e32 v89, v0
	v_mov_b32_e32 v90, v0
	v_mov_b32_e32 v91, v0
	v_mov_b32_e32 v96, v0
	v_mov_b32_e32 v97, v0
	v_mov_b32_e32 v98, v0
	v_mov_b32_e32 v99, v0
	v_mov_b32_e32 v112, v0
	v_mov_b32_e32 v113, v0
	v_mov_b32_e32 v114, v0
	v_mov_b32_e32 v115, v0
	v_mov_b32_e32 v116, v0
	v_mov_b32_e32 v117, v0
	v_mov_b32_e32 v118, v0
	v_mov_b32_e32 v119, v0
	v_mov_b32_e32 v76, v0
	v_mov_b32_e32 v77, v0
	v_mov_b32_e32 v78, v0
	v_mov_b32_e32 v79, v0
	v_mov_b32_e32 v84, v0
	v_mov_b32_e32 v85, v0
	v_mov_b32_e32 v86, v0
	v_mov_b32_e32 v87, v0
	v_mov_b32_e32 v92, v0
	v_mov_b32_e32 v93, v0
	v_mov_b32_e32 v94, v0
	v_mov_b32_e32 v95, v0
	v_mov_b32_e32 v100, v0
	v_mov_b32_e32 v101, v0
	v_mov_b32_e32 v102, v0
	v_mov_b32_e32 v103, v0
	v_mov_b32_e32 v104, v0
	v_mov_b32_e32 v105, v0
	v_mov_b32_e32 v106, v0
	v_mov_b32_e32 v107, v0
	v_mov_b32_e32 v108, v0
	v_mov_b32_e32 v109, v0
	v_mov_b32_e32 v110, v0
	v_mov_b32_e32 v111, v0
	v_mov_b32_e32 v120, v0
	v_mov_b32_e32 v121, v0
	v_mov_b32_e32 v122, v0
	v_mov_b32_e32 v123, v0
	v_mov_b32_e32 v124, v0
	v_mov_b32_e32 v125, v0
	v_mov_b32_e32 v126, v0
	v_mov_b32_e32 v127, v0
	.p2align	6

; template <class Epi, class Sched = StaticOrder>
; DI void gemm_phase(LAS unsigned char* lds, const Gemm g, const Sched& S, const Epi& E) {
;     ...
;     const bool has_next = S.next(ui + 1, nxt);
;     const char* nA = has_next ? (const char*)g.A + (size_t)nxt.pm * tstep : cA; const char* nB = has_next ? (const char*)g.Bt + (size_t)nxt.pn * tstep : cB;
;     ...
; #pragma unroll
;     for (int a = 0; a < 2; ++a)
; #pragma unroll
;       for (int b = 0; b < 2; ++b)
; #pragma unroll
;         for (int m = 0; m < 4; ++m)
; #pragma unroll
;           for (int n = 0; n < 2; ++n) acc[a][b][m][n] = (f32x4){0.f, 0.f, 0.f, 0.f};
;     cur = nxt; cA = nA; cB = nB; ++ui;
.LBB0_727:
	s_ashr_i32 s17, s16, 31
	v_cmp_lt_i64_e32 vcc, s[18:19], v[188:189]
	s_lshl_b64 s[18:19], s[16:17], 20
	s_add_u32 s18, s30, s18
	s_addc_u32 s19, s31, s19
	s_and_b64 s[20:21], vcc, exec
	s_cselect_b32 s17, s19, s23
	s_cselect_b32 s43, s18, s22
	s_ashr_i32 s15, s14, 31
	s_lshl_b64 s[20:21], s[14:15], 20
	s_add_u32 s20, s33, s20
	s_addc_u32 s21, s34, s21
	s_and_b64 s[26:27], vcc, exec
	s_cselect_b32 s15, s21, s25
	s_cselect_b32 s44, s20, s24
	s_add_u32 s22, s22, 0x80080
	s_addc_u32 s23, s23, 0
	s_add_u32 s45, s24, 0x100
	v_mov_b32_e32 v0, 0
	s_addc_u32 s52, s25, 0
	s_mov_b32 s53, -2
	s_waitcnt lgkmcnt(0)
	v_mov_b32_e32 v1, v0
	v_mov_b32_e32 v2, v0
	v_mov_b32_e32 v3, v0
	v_mov_b32_e32 v4, v0
	v_mov_b32_e32 v5, v0
	v_mov_b32_e32 v6, v0
	v_mov_b32_e32 v7, v0
	v_mov_b32_e32 v16, v0
	v_mov_b32_e32 v17, v0
	v_mov_b32_e32 v18, v0
	v_mov_b32_e32 v19, v0
	v_mov_b32_e32 v20, v0
	v_mov_b32_e32 v21, v0
	v_mov_b32_e32 v22, v0
	v_mov_b32_e32 v23, v0
	v_mov_b32_e32 v32, v0
	v_mov_b32_e32 v33, v0
	v_mov_b32_e32 v34, v0
	v_mov_b32_e32 v35, v0
	v_mov_b32_e32 v36, v0
	v_mov_b32_e32 v37, v0
	v_mov_b32_e32 v38, v0
	v_mov_b32_e32 v39, v0
	v_mov_b32_e32 v48, v0
	v_mov_b32_e32 v49, v0
	v_mov_b32_e32 v50, v0
	v_mov_b32_e32 v51, v0
	v_mov_b32_e32 v52, v0
	v_mov_b32_e32 v53, v0
	v_mov_b32_e32 v54, v0
	v_mov_b32_e32 v55, v0
	v_mov_b32_e32 v8, v0
	v_mov_b32_e32 v9, v0
	v_mov_b32_e32 v10, v0
	v_mov_b32_e32 v11, v0
	v_mov_b32_e32 v12, v0
	v_mov_b32_e32 v13, v0
	v_mov_b32_e32 v14, v0
	v_mov_b32_e32 v15, v0
	v_mov_b32_e32 v24, v0
	v_mov_b32_e32 v25, v0
	v_mov_b32_e32 v26, v0
	v_mov_b32_e32 v27, v0
	v_mov_b32_e32 v28, v0
	v_mov_b32_e32 v29, v0
	v_mov_b32_e32 v30, v0
	v_mov_b32_e32 v31, v0
	v_mov_b32_e32 v40, v0
	v_mov_b32_e32 v41, v0
	v_mov_b32_e32 v42, v0
	v_mov_b32_e32 v43, v0
	v_mov_b32_e32 v44, v0
	v_mov_b32_e32 v45, v0
	v_mov_b32_e32 v46, v0
	v_mov_b32_e32 v47, v0
	v_mov_b32_e32 v56, v0
	v_mov_b32_e32 v57, v0
	v_mov_b32_e32 v58, v0
	v_mov_b32_e32 v59, v0
	v_mov_b32_e32 v60, v0
	v_mov_b32_e32 v61, v0
	v_mov_b32_e32 v62, v0
	v_mov_b32_e32 v63, v0
	v_mov_b32_e32 v64, v0
	v_mov_b32_e32 v65, v0
	v_mov_b32_e32 v66, v0
	v_mov_b32_e32 v67, v0
	v_mov_b32_e32 v68, v0
	v_mov_b32_e32 v69, v0
	v_mov_b32_e32 v70, v0
	v_mov_b32_e32 v71, v0
	v_mov_b32_e32 v80, v0
	v_mov_b32_e32 v81, v0
	v_mov_b32_e32 v82, v0
	v_mov_b32_e32 v83, v0
	v_mov_b32_e32 v84, v0
	v_mov_b32_e32 v85, v0
	v_mov_b32_e32 v86, v0
	v_mov_b32_e32 v87, v0
	v_mov_b32_e32 v96, v0
	v_mov_b32_e32 v97, v0
	v_mov_b32_e32 v98, v0
	v_mov_b32_e32 v99, v0
	v_mov_b32_e32 v100, v0
	v_mov_b32_e32 v101, v0
	v_mov_b32_e32 v102, v0
	v_mov_b32_e32 v103, v0
	v_mov_b32_e32 v112, v0
	v_mov_b32_e32 v113, v0
	v_mov_b32_e32 v114, v0
	v_mov_b32_e32 v115, v0
	v_mov_b32_e32 v116, v0
	v_mov_b32_e32 v117, v0
	v_mov_b32_e32 v118, v0
	v_mov_b32_e32 v119, v0
	v_mov_b32_e32 v72, v0
	v_mov_b32_e32 v73, v0
	v_mov_b32_e32 v74, v0
	v_mov_b32_e32 v75, v0
	v_mov_b32_e32 v76, v0
	v_mov_b32_e32 v77, v0
	v_mov_b32_e32 v78, v0
	v_mov_b32_e32 v79, v0
	v_mov_b32_e32 v88, v0
	v_mov_b32_e32 v89, v0
	v_mov_b32_e32 v90, v0
	v_mov_b32_e32 v91, v0
	v_mov_b32_e32 v92, v0
	v_mov_b32_e32 v93, v0
	v_mov_b32_e32 v94, v0
	v_mov_b32_e32 v95, v0
	v_mov_b32_e32 v104, v0
	v_mov_b32_e32 v105, v0
	v_mov_b32_e32 v106, v0
	v_mov_b32_e32 v107, v0
	v_mov_b32_e32 v108, v0
	v_mov_b32_e32 v109, v0
	v_mov_b32_e32 v110, v0
	v_mov_b32_e32 v111, v0
	v_mov_b32_e32 v120, v0
	v_mov_b32_e32 v121, v0
	v_mov_b32_e32 v122, v0
	v_mov_b32_e32 v123, v0
	v_mov_b32_e32 v124, v0
	v_mov_b32_e32 v125, v0
	v_mov_b32_e32 v126, v0
	v_mov_b32_e32 v127, v0
	.p2align	6

; template <class Epi, class Sched = StaticOrder>
; DI void gemm_phase(LAS unsigned char* lds, const Gemm g, const Sched& S, const Epi& E) {
;     ...
;     const bool has_next = S.next(ui + 1, nxt);
;     const char* nA = has_next ? (const char*)g.A + (size_t)nxt.pm * tstep : cA; const char* nB = has_next ? (const char*)g.Bt + (size_t)nxt.pn * tstep : cB;
;     ...
; #pragma unroll
;     for (int a = 0; a < 2; ++a)
; #pragma unroll
;       for (int b = 0; b < 2; ++b)
; #pragma unroll
;         for (int m = 0; m < 4; ++m)
; #pragma unroll
;           for (int n = 0; n < 2; ++n) acc[a][b][m][n] = (f32x4){0.f, 0.f, 0.f, 0.f};
;     cur = nxt; cA = nA; cB = nB; ++ui;
.LBB0_810:
	s_ashr_i32 s37, s36, 31
	v_cmp_lt_i64_e32 vcc, s[38:39], v[174:175]
	s_lshl_b64 s[38:39], s[36:37], 20
	s_add_u32 s38, s77, s38
	s_addc_u32 s39, s78, s39
	s_and_b64 s[40:41], vcc, exec
	s_cselect_b32 s37, s39, s15
	s_cselect_b32 s42, s38, s14
	s_ashr_i32 s35, s34, 31
	s_lshl_b64 s[40:41], s[34:35], 20
	s_add_u32 s40, s79, s40
	s_addc_u32 s41, s80, s41
	s_and_b64 s[44:45], vcc, exec
	s_cselect_b32 s35, s41, s47
	s_cselect_b32 s43, s40, s46
	s_add_u32 s14, s14, 0x80080
	s_addc_u32 s15, s15, 0
	s_add_u32 s44, s46, 0x100
	v_mov_b32_e32 v0, 0
	s_addc_u32 s45, s47, 0
	s_mov_b32 s52, -2
	v_mov_b32_e32 v1, v0
	v_mov_b32_e32 v2, v0
	v_mov_b32_e32 v3, v0
	v_mov_b32_e32 v4, v0
	v_mov_b32_e32 v5, v0
	v_mov_b32_e32 v6, v0
	v_mov_b32_e32 v7, v0
	v_mov_b32_e32 v8, v0
	v_mov_b32_e32 v9, v0
	v_mov_b32_e32 v10, v0
	v_mov_b32_e32 v11, v0
	v_mov_b32_e32 v24, v0
	v_mov_b32_e32 v25, v0
	v_mov_b32_e32 v26, v0
	v_mov_b32_e32 v27, v0
	v_mov_b32_e32 v32, v0
	v_mov_b32_e32 v33, v0
	v_mov_b32_e32 v34, v0
	v_mov_b32_e32 v35, v0
	v_mov_b32_e32 v40, v0
	v_mov_b32_e32 v41, v0
	v_mov_b32_e32 v42, v0
	v_mov_b32_e32 v43, v0
	v_mov_b32_e32 v52, v0
	v_mov_b32_e32 v53, v0
	v_mov_b32_e32 v54, v0
	v_mov_b32_e32 v55, v0
	v_mov_b32_e32 v56, v0
	v_mov_b32_e32 v57, v0
	v_mov_b32_e32 v58, v0
	v_mov_b32_e32 v59, v0
	v_mov_b32_e32 v12, v0
	v_mov_b32_e32 v13, v0
	v_mov_b32_e32 v14, v0
	v_mov_b32_e32 v15, v0
	v_mov_b32_e32 v16, v0
	v_mov_b32_e32 v17, v0
	v_mov_b32_e32 v18, v0
	v_mov_b32_e32 v19, v0
	v_mov_b32_e32 v20, v0
	v_mov_b32_e32 v21, v0
	v_mov_b32_e32 v22, v0
	v_mov_b32_e32 v23, v0
	v_mov_b32_e32 v28, v0
	v_mov_b32_e32 v29, v0
	v_mov_b32_e32 v30, v0
	v_mov_b32_e32 v31, v0
	v_mov_b32_e32 v36, v0
	v_mov_b32_e32 v37, v0
	v_mov_b32_e32 v38, v0
	v_mov_b32_e32 v39, v0
	v_mov_b32_e32 v44, v0
	v_mov_b32_e32 v45, v0
	v_mov_b32_e32 v46, v0
	v_mov_b32_e32 v47, v0
	v_mov_b32_e32 v48, v0
	v_mov_b32_e32 v49, v0
	v_mov_b32_e32 v50, v0
	v_mov_b32_e32 v51, v0
	v_mov_b32_e32 v60, v0
	v_mov_b32_e32 v61, v0
	v_mov_b32_e32 v62, v0
	v_mov_b32_e32 v63, v0
	v_mov_b32_e32 v88, v0
	v_mov_b32_e32 v89, v0
	v_mov_b32_e32 v90, v0
	v_mov_b32_e32 v91, v0
	v_mov_b32_e32 v100, v0
	v_mov_b32_e32 v101, v0
	v_mov_b32_e32 v102, v0
	v_mov_b32_e32 v103, v0
	v_mov_b32_e32 v104, v0
	v_mov_b32_e32 v105, v0
	v_mov_b32_e32 v106, v0
	v_mov_b32_e32 v107, v0
	v_mov_b32_e32 v120, v0
	v_mov_b32_e32 v121, v0
	v_mov_b32_e32 v122, v0
	v_mov_b32_e32 v123, v0
	v_mov_b32_e32 v128, v0
	v_mov_b32_e32 v129, v0
	v_mov_b32_e32 v130, v0
	v_mov_b32_e32 v131, v0
	v_mov_b32_e32 v136, v0
	v_mov_b32_e32 v137, v0
	v_mov_b32_e32 v138, v0
	v_mov_b32_e32 v139, v0
	v_mov_b32_e32 v148, v0
	v_mov_b32_e32 v149, v0
	v_mov_b32_e32 v150, v0
	v_mov_b32_e32 v151, v0
	v_mov_b32_e32 v152, v0
	v_mov_b32_e32 v153, v0
	v_mov_b32_e32 v154, v0
	v_mov_b32_e32 v155, v0
	v_mov_b32_e32 v108, v0
	v_mov_b32_e32 v109, v0
	v_mov_b32_e32 v110, v0
	v_mov_b32_e32 v111, v0
	v_mov_b32_e32 v112, v0
	v_mov_b32_e32 v113, v0
	v_mov_b32_e32 v114, v0
	v_mov_b32_e32 v115, v0
	v_mov_b32_e32 v116, v0
	v_mov_b32_e32 v117, v0
	v_mov_b32_e32 v118, v0
	v_mov_b32_e32 v119, v0
	v_mov_b32_e32 v124, v0
	v_mov_b32_e32 v125, v0
	v_mov_b32_e32 v126, v0
	v_mov_b32_e32 v127, v0
	v_mov_b32_e32 v132, v0
	v_mov_b32_e32 v133, v0
	v_mov_b32_e32 v134, v0
	v_mov_b32_e32 v135, v0
	v_mov_b32_e32 v140, v0
	v_mov_b32_e32 v141, v0
	v_mov_b32_e32 v142, v0
	v_mov_b32_e32 v143, v0
	v_mov_b32_e32 v144, v0
	v_mov_b32_e32 v145, v0
	v_mov_b32_e32 v146, v0
	v_mov_b32_e32 v147, v0
	v_mov_b32_e32 v156, v0
	v_mov_b32_e32 v157, v0
	v_mov_b32_e32 v158, v0
	v_mov_b32_e32 v159, v0
	.p2align	6

; template <class Epi, class Sched = StaticOrder>
; DI void gemm_phase(LAS unsigned char* lds, const Gemm g, const Sched& S, const Epi& E) {
;     ...
;     const bool has_next = S.next(ui + 1, nxt);
;     const char* nA = has_next ? (const char*)g.A + (size_t)nxt.pm * tstep : cA; const char* nB = has_next ? (const char*)g.Bt + (size_t)nxt.pn * tstep : cB;
;     for (int t = 0; t < nt; t += 2) {
;       const bool last = (t == nt - 2);
;       const char* a1 = cA + (size_t)(t + 1) * kstep;
;       const char* a2 = last ? nA : cA + (size_t)(t + 2) * kstep; const char* b2 = last ? nB : cB + (size_t)(t + 2) * kstep;
;       const char* a3 = a2 + kstep; const char* b3 = b2 + kstep;
;     ...
; #pragma unroll
;     for (int a = 0; a < 2; ++a)
; #pragma unroll
;       for (int b = 0; b < 2; ++b)
; #pragma unroll
;         for (int m = 0; m < 4; ++m)
; #pragma unroll
;           for (int n = 0; n < 2; ++n) acc[a][b][m][n] = (f32x4){0.f, 0.f, 0.f, 0.f};
;     cur = nxt; cA = nA; cB = nB; ++ui;
.LBB0_960:
	s_add_u32 s18, s18, 0x160080
	s_addc_u32 s19, s19, 0
	s_add_u32 s42, s20, 0x100
	v_mov_b32_e32 v0, 0
	s_addc_u32 s43, s21, 0
	s_mov_b32 s44, -2
	s_waitcnt lgkmcnt(0)
	v_mov_b32_e32 v1, v0
	v_mov_b32_e32 v2, v0
	v_mov_b32_e32 v3, v0
	v_mov_b32_e32 v4, v0
	v_mov_b32_e32 v5, v0
	v_mov_b32_e32 v6, v0
	v_mov_b32_e32 v7, v0
	v_mov_b32_e32 v16, v0
	v_mov_b32_e32 v17, v0
	v_mov_b32_e32 v18, v0
	v_mov_b32_e32 v19, v0
	v_mov_b32_e32 v20, v0
	v_mov_b32_e32 v21, v0
	v_mov_b32_e32 v22, v0
	v_mov_b32_e32 v23, v0
	v_mov_b32_e32 v32, v0
	v_mov_b32_e32 v33, v0
	v_mov_b32_e32 v34, v0
	v_mov_b32_e32 v35, v0
	v_mov_b32_e32 v36, v0
	v_mov_b32_e32 v37, v0
	v_mov_b32_e32 v38, v0
	v_mov_b32_e32 v39, v0
	v_mov_b32_e32 v48, v0
	v_mov_b32_e32 v49, v0
	v_mov_b32_e32 v50, v0
	v_mov_b32_e32 v51, v0
	v_mov_b32_e32 v52, v0
	v_mov_b32_e32 v53, v0
	v_mov_b32_e32 v54, v0
	v_mov_b32_e32 v55, v0
	v_mov_b32_e32 v8, v0
	v_mov_b32_e32 v9, v0
	v_mov_b32_e32 v10, v0
	v_mov_b32_e32 v11, v0
	v_mov_b32_e32 v12, v0
	v_mov_b32_e32 v13, v0
	v_mov_b32_e32 v14, v0
	v_mov_b32_e32 v15, v0
	v_mov_b32_e32 v24, v0
	v_mov_b32_e32 v25, v0
	v_mov_b32_e32 v26, v0
	v_mov_b32_e32 v27, v0
	v_mov_b32_e32 v28, v0
	v_mov_b32_e32 v29, v0
	v_mov_b32_e32 v30, v0
	v_mov_b32_e32 v31, v0
	v_mov_b32_e32 v40, v0
	v_mov_b32_e32 v41, v0
	v_mov_b32_e32 v42, v0
	v_mov_b32_e32 v43, v0
	v_mov_b32_e32 v44, v0
	v_mov_b32_e32 v45, v0
	v_mov_b32_e32 v46, v0
	v_mov_b32_e32 v47, v0
	v_mov_b32_e32 v56, v0
	v_mov_b32_e32 v57, v0
	v_mov_b32_e32 v58, v0
	v_mov_b32_e32 v59, v0
	v_mov_b32_e32 v60, v0
	v_mov_b32_e32 v61, v0
	v_mov_b32_e32 v62, v0
	v_mov_b32_e32 v63, v0
	v_mov_b32_e32 v64, v0
	v_mov_b32_e32 v65, v0
	v_mov_b32_e32 v66, v0
	v_mov_b32_e32 v67, v0
	v_mov_b32_e32 v68, v0
	v_mov_b32_e32 v69, v0
	v_mov_b32_e32 v70, v0
	v_mov_b32_e32 v71, v0
	v_mov_b32_e32 v80, v0
	v_mov_b32_e32 v81, v0
	v_mov_b32_e32 v82, v0
	v_mov_b32_e32 v83, v0
	v_mov_b32_e32 v84, v0
	v_mov_b32_e32 v85, v0
	v_mov_b32_e32 v86, v0
	v_mov_b32_e32 v87, v0
	v_mov_b32_e32 v96, v0
	v_mov_b32_e32 v97, v0
	v_mov_b32_e32 v98, v0
	v_mov_b32_e32 v99, v0
	v_mov_b32_e32 v100, v0
	v_mov_b32_e32 v101, v0
	v_mov_b32_e32 v102, v0
	v_mov_b32_e32 v103, v0
	v_mov_b32_e32 v112, v0
	v_mov_b32_e32 v113, v0
	v_mov_b32_e32 v114, v0
	v_mov_b32_e32 v115, v0
	v_mov_b32_e32 v116, v0
	v_mov_b32_e32 v117, v0
	v_mov_b32_e32 v118, v0
	v_mov_b32_e32 v119, v0
	v_mov_b32_e32 v72, v0
	v_mov_b32_e32 v73, v0
	v_mov_b32_e32 v74, v0
	v_mov_b32_e32 v75, v0
	v_mov_b32_e32 v76, v0
	v_mov_b32_e32 v77, v0
	v_mov_b32_e32 v78, v0
	v_mov_b32_e32 v79, v0
	v_mov_b32_e32 v88, v0
	v_mov_b32_e32 v89, v0
	v_mov_b32_e32 v90, v0
	v_mov_b32_e32 v91, v0
	v_mov_b32_e32 v92, v0
	v_mov_b32_e32 v93, v0
	v_mov_b32_e32 v94, v0
	v_mov_b32_e32 v95, v0
	v_mov_b32_e32 v104, v0
	v_mov_b32_e32 v105, v0
	v_mov_b32_e32 v106, v0
	v_mov_b32_e32 v107, v0
	v_mov_b32_e32 v108, v0
	v_mov_b32_e32 v109, v0
	v_mov_b32_e32 v110, v0
	v_mov_b32_e32 v111, v0
	v_mov_b32_e32 v120, v0
	v_mov_b32_e32 v121, v0
	v_mov_b32_e32 v122, v0
	v_mov_b32_e32 v123, v0
	v_mov_b32_e32 v124, v0
	v_mov_b32_e32 v125, v0
	v_mov_b32_e32 v126, v0
	v_mov_b32_e32 v127, v0
	.p2align	6

; template <class Epi, class Sched = StaticOrder>
; DI void gemm_phase(LAS unsigned char* lds, const Gemm g, const Sched& S, const Epi& E) {
;     ...
;     const bool has_next = S.next(ui + 1, nxt);
;     const char* nA = has_next ? (const char*)g.A + (size_t)nxt.pm * tstep : cA; const char* nB = has_next ? (const char*)g.Bt + (size_t)nxt.pn * tstep : cB;
;     ...
; #pragma unroll
;     for (int a = 0; a < 2; ++a)
; #pragma unroll
;       for (int b = 0; b < 2; ++b)
; #pragma unroll
;         for (int m = 0; m < 4; ++m)
; #pragma unroll
;           for (int n = 0; n < 2; ++n) acc[a][b][m][n] = (f32x4){0.f, 0.f, 0.f, 0.f};
;     cur = nxt; cA = nA; cB = nB; ++ui;
.LBB0_1051:
	s_ashr_i32 s41, s40, 31
	s_lshl_b64 s[42:43], s[40:41], 20
	s_add_u32 s88, s66, s42
	s_addc_u32 s89, s67, s43
	s_and_b64 s[42:43], s[64:65], exec
	s_cselect_b32 s41, s89, s11
	s_cselect_b32 s42, s88, s10
	s_ashr_i32 s87, s86, 31
	s_lshl_b64 s[44:45], s[86:87], 20
	s_add_u32 s90, s68, s44
	s_addc_u32 s91, s69, s45
	s_and_b64 s[44:45], s[64:65], exec
	s_cselect_b32 s43, s91, s13
	s_cselect_b32 s44, s90, s12
	s_add_u32 s10, s10, 0x80080
	s_addc_u32 s11, s11, 0
	s_add_u32 s45, s12, 0x100
	v_mov_b32_e32 v0, 0
	s_addc_u32 s49, s13, 0
	s_mov_b32 s52, -2
	v_mov_b32_e32 v1, v0
	v_mov_b32_e32 v2, v0
	v_mov_b32_e32 v3, v0
	v_mov_b32_e32 v4, v0
	v_mov_b32_e32 v5, v0
	v_mov_b32_e32 v6, v0
	v_mov_b32_e32 v7, v0
	v_mov_b32_e32 v16, v0
	v_mov_b32_e32 v17, v0
	v_mov_b32_e32 v18, v0
	v_mov_b32_e32 v19, v0
	v_mov_b32_e32 v20, v0
	v_mov_b32_e32 v21, v0
	v_mov_b32_e32 v22, v0
	v_mov_b32_e32 v23, v0
	v_mov_b32_e32 v32, v0
	v_mov_b32_e32 v33, v0
	v_mov_b32_e32 v34, v0
	v_mov_b32_e32 v35, v0
	v_mov_b32_e32 v36, v0
	v_mov_b32_e32 v37, v0
	v_mov_b32_e32 v38, v0
	v_mov_b32_e32 v39, v0
	v_mov_b32_e32 v44, v0
	v_mov_b32_e32 v45, v0
	v_mov_b32_e32 v46, v0
	v_mov_b32_e32 v47, v0
	v_mov_b32_e32 v52, v0
	v_mov_b32_e32 v53, v0
	v_mov_b32_e32 v54, v0
	v_mov_b32_e32 v55, v0
	v_mov_b32_e32 v8, v0
	v_mov_b32_e32 v9, v0
	v_mov_b32_e32 v10, v0
	v_mov_b32_e32 v11, v0
	v_mov_b32_e32 v12, v0
	v_mov_b32_e32 v13, v0
	v_mov_b32_e32 v14, v0
	v_mov_b32_e32 v15, v0
	v_mov_b32_e32 v24, v0
	v_mov_b32_e32 v25, v0
	v_mov_b32_e32 v26, v0
	v_mov_b32_e32 v27, v0
	v_mov_b32_e32 v28, v0
	v_mov_b32_e32 v29, v0
	v_mov_b32_e32 v30, v0
	v_mov_b32_e32 v31, v0
	v_mov_b32_e32 v40, v0
	v_mov_b32_e32 v41, v0
	v_mov_b32_e32 v42, v0
	v_mov_b32_e32 v43, v0
	v_mov_b32_e32 v48, v0
	v_mov_b32_e32 v49, v0
	v_mov_b32_e32 v50, v0
	v_mov_b32_e32 v51, v0
	v_mov_b32_e32 v56, v0
	v_mov_b32_e32 v57, v0
	v_mov_b32_e32 v58, v0
	v_mov_b32_e32 v59, v0
	v_mov_b32_e32 v60, v0
	v_mov_b32_e32 v61, v0
	v_mov_b32_e32 v62, v0
	v_mov_b32_e32 v63, v0
	v_mov_b32_e32 v64, v0
	v_mov_b32_e32 v65, v0
	v_mov_b32_e32 v66, v0
	v_mov_b32_e32 v67, v0
	v_mov_b32_e32 v68, v0
	v_mov_b32_e32 v69, v0
	v_mov_b32_e32 v70, v0
	v_mov_b32_e32 v71, v0
	v_mov_b32_e32 v76, v0
	v_mov_b32_e32 v77, v0
	v_mov_b32_e32 v78, v0
	v_mov_b32_e32 v79, v0
	v_mov_b32_e32 v80, v0
	v_mov_b32_e32 v81, v0
	v_mov_b32_e32 v82, v0
	v_mov_b32_e32 v83, v0
	v_mov_b32_e32 v96, v0
	v_mov_b32_e32 v97, v0
	v_mov_b32_e32 v98, v0
	v_mov_b32_e32 v99, v0
	v_mov_b32_e32 v100, v0
	v_mov_b32_e32 v101, v0
	v_mov_b32_e32 v102, v0
	v_mov_b32_e32 v103, v0
	v_mov_b32_e32 v108, v0
	v_mov_b32_e32 v109, v0
	v_mov_b32_e32 v110, v0
	v_mov_b32_e32 v111, v0
	v_mov_b32_e32 v112, v0
	v_mov_b32_e32 v113, v0
	v_mov_b32_e32 v114, v0
	v_mov_b32_e32 v115, v0
	v_mov_b32_e32 v72, v0
	v_mov_b32_e32 v73, v0
	v_mov_b32_e32 v74, v0
	v_mov_b32_e32 v75, v0
	v_mov_b32_e32 v84, v0
	v_mov_b32_e32 v85, v0
	v_mov_b32_e32 v86, v0
	v_mov_b32_e32 v87, v0
	v_mov_b32_e32 v88, v0
	v_mov_b32_e32 v89, v0
	v_mov_b32_e32 v90, v0
	v_mov_b32_e32 v91, v0
	v_mov_b32_e32 v92, v0
	v_mov_b32_e32 v93, v0
	v_mov_b32_e32 v94, v0
	v_mov_b32_e32 v95, v0
	v_mov_b32_e32 v104, v0
	v_mov_b32_e32 v105, v0
	v_mov_b32_e32 v106, v0
	v_mov_b32_e32 v107, v0
	v_mov_b32_e32 v116, v0
	v_mov_b32_e32 v117, v0
	v_mov_b32_e32 v118, v0
	v_mov_b32_e32 v119, v0
	v_mov_b32_e32 v120, v0
	v_mov_b32_e32 v121, v0
	v_mov_b32_e32 v122, v0
	v_mov_b32_e32 v123, v0
	v_mov_b32_e32 v124, v0
	v_mov_b32_e32 v125, v0
	v_mov_b32_e32 v126, v0
	v_mov_b32_e32 v127, v0
	.p2align	6

; template <class Epi, class Sched = StaticOrder>
; DI void gemm_phase(LAS unsigned char* lds, const Gemm g, const Sched& S, const Epi& E) {
;     ...
;     const bool has_next = S.next(ui + 1, nxt);
;     const char* nA = has_next ? (const char*)g.A + (size_t)nxt.pm * tstep : cA; const char* nB = has_next ? (const char*)g.Bt + (size_t)nxt.pn * tstep : cB;
;     ...
; #pragma unroll
;     for (int a = 0; a < 2; ++a)
; #pragma unroll
;       for (int b = 0; b < 2; ++b)
; #pragma unroll
;         for (int m = 0; m < 4; ++m)
; #pragma unroll
;           for (int n = 0; n < 2; ++n) acc[a][b][m][n] = (f32x4){0.f, 0.f, 0.f, 0.f};
;     cur = nxt; cA = nA; cB = nB; ++ui;
.LBB0_1193:
	s_ashr_i32 s17, s16, 31
	v_cmp_lt_i64_e32 vcc, s[18:19], v[188:189]
	s_lshl_b64 s[18:19], s[16:17], 20
	s_add_u32 s18, s30, s18
	s_addc_u32 s19, s31, s19
	s_and_b64 s[20:21], vcc, exec
	s_cselect_b32 s17, s19, s23
	s_cselect_b32 s43, s18, s22
	s_ashr_i32 s15, s14, 31
	s_lshl_b64 s[20:21], s[14:15], 20
	s_add_u32 s20, s33, s20
	s_addc_u32 s21, s34, s21
	s_and_b64 s[26:27], vcc, exec
	s_cselect_b32 s15, s21, s25
	s_cselect_b32 s51, s20, s24
	s_add_u32 s22, s22, 0x80080
	s_addc_u32 s23, s23, 0
	s_add_u32 s52, s24, 0x100
	v_mov_b32_e32 v0, 0
	s_addc_u32 s53, s25, 0
	s_mov_b32 s54, -2
	s_waitcnt lgkmcnt(0)
	v_mov_b32_e32 v1, v0
	v_mov_b32_e32 v2, v0
	v_mov_b32_e32 v3, v0
	v_mov_b32_e32 v4, v0
	v_mov_b32_e32 v5, v0
	v_mov_b32_e32 v6, v0
	v_mov_b32_e32 v7, v0
	v_mov_b32_e32 v16, v0
	v_mov_b32_e32 v17, v0
	v_mov_b32_e32 v18, v0
	v_mov_b32_e32 v19, v0
	v_mov_b32_e32 v20, v0
	v_mov_b32_e32 v21, v0
	v_mov_b32_e32 v22, v0
	v_mov_b32_e32 v23, v0
	v_mov_b32_e32 v32, v0
	v_mov_b32_e32 v33, v0
	v_mov_b32_e32 v34, v0
	v_mov_b32_e32 v35, v0
	v_mov_b32_e32 v36, v0
	v_mov_b32_e32 v37, v0
	v_mov_b32_e32 v38, v0
	v_mov_b32_e32 v39, v0
	v_mov_b32_e32 v48, v0
	v_mov_b32_e32 v49, v0
	v_mov_b32_e32 v50, v0
	v_mov_b32_e32 v51, v0
	v_mov_b32_e32 v52, v0
	v_mov_b32_e32 v53, v0
	v_mov_b32_e32 v54, v0
	v_mov_b32_e32 v55, v0
	v_mov_b32_e32 v8, v0
	v_mov_b32_e32 v9, v0
	v_mov_b32_e32 v10, v0
	v_mov_b32_e32 v11, v0
	v_mov_b32_e32 v12, v0
	v_mov_b32_e32 v13, v0
	v_mov_b32_e32 v14, v0
	v_mov_b32_e32 v15, v0
	v_mov_b32_e32 v24, v0
	v_mov_b32_e32 v25, v0
	v_mov_b32_e32 v26, v0
	v_mov_b32_e32 v27, v0
	v_mov_b32_e32 v28, v0
	v_mov_b32_e32 v29, v0
	v_mov_b32_e32 v30, v0
	v_mov_b32_e32 v31, v0
	v_mov_b32_e32 v40, v0
	v_mov_b32_e32 v41, v0
	v_mov_b32_e32 v42, v0
	v_mov_b32_e32 v43, v0
	v_mov_b32_e32 v44, v0
	v_mov_b32_e32 v45, v0
	v_mov_b32_e32 v46, v0
	v_mov_b32_e32 v47, v0
	v_mov_b32_e32 v56, v0
	v_mov_b32_e32 v57, v0
	v_mov_b32_e32 v58, v0
	v_mov_b32_e32 v59, v0
	v_mov_b32_e32 v60, v0
	v_mov_b32_e32 v61, v0
	v_mov_b32_e32 v62, v0
	v_mov_b32_e32 v63, v0
	v_mov_b32_e32 v64, v0
	v_mov_b32_e32 v65, v0
	v_mov_b32_e32 v66, v0
	v_mov_b32_e32 v67, v0
	v_mov_b32_e32 v68, v0
	v_mov_b32_e32 v69, v0
	v_mov_b32_e32 v70, v0
	v_mov_b32_e32 v71, v0
	v_mov_b32_e32 v80, v0
	v_mov_b32_e32 v81, v0
	v_mov_b32_e32 v82, v0
	v_mov_b32_e32 v83, v0
	v_mov_b32_e32 v84, v0
	v_mov_b32_e32 v85, v0
	v_mov_b32_e32 v86, v0
	v_mov_b32_e32 v87, v0
	v_mov_b32_e32 v96, v0
	v_mov_b32_e32 v97, v0
	v_mov_b32_e32 v98, v0
	v_mov_b32_e32 v99, v0
	v_mov_b32_e32 v100, v0
	v_mov_b32_e32 v101, v0
	v_mov_b32_e32 v102, v0
	v_mov_b32_e32 v103, v0
	v_mov_b32_e32 v112, v0
	v_mov_b32_e32 v113, v0
	v_mov_b32_e32 v114, v0
	v_mov_b32_e32 v115, v0
	v_mov_b32_e32 v116, v0
	v_mov_b32_e32 v117, v0
	v_mov_b32_e32 v118, v0
	v_mov_b32_e32 v119, v0
	v_mov_b32_e32 v72, v0
	v_mov_b32_e32 v73, v0
	v_mov_b32_e32 v74, v0
	v_mov_b32_e32 v75, v0
	v_mov_b32_e32 v76, v0
	v_mov_b32_e32 v77, v0
	v_mov_b32_e32 v78, v0
	v_mov_b32_e32 v79, v0
	v_mov_b32_e32 v88, v0
	v_mov_b32_e32 v89, v0
	v_mov_b32_e32 v90, v0
	v_mov_b32_e32 v91, v0
	v_mov_b32_e32 v92, v0
	v_mov_b32_e32 v93, v0
	v_mov_b32_e32 v94, v0
	v_mov_b32_e32 v95, v0
	v_mov_b32_e32 v104, v0
	v_mov_b32_e32 v105, v0
	v_mov_b32_e32 v106, v0
	v_mov_b32_e32 v107, v0
	v_mov_b32_e32 v108, v0
	v_mov_b32_e32 v109, v0
	v_mov_b32_e32 v110, v0
	v_mov_b32_e32 v111, v0
	v_mov_b32_e32 v120, v0
	v_mov_b32_e32 v121, v0
	v_mov_b32_e32 v122, v0
	v_mov_b32_e32 v123, v0
	v_mov_b32_e32 v124, v0
	v_mov_b32_e32 v125, v0
	v_mov_b32_e32 v126, v0
	v_mov_b32_e32 v127, v0
	.p2align	6

; template <class Epi, class Sched = StaticOrder>
; DI void gemm_phase(LAS unsigned char* lds, const Gemm g, const Sched& S, const Epi& E) {
;     ...
;     const bool has_next = S.next(ui + 1, nxt);
;     const char* nA = has_next ? (const char*)g.A + (size_t)nxt.pm * tstep : cA; const char* nB = has_next ? (const char*)g.Bt + (size_t)nxt.pn * tstep : cB;
;     for (int t = 0; t < nt; t += 2) {
;       const bool last = (t == nt - 2);
;       const char* a1 = cA + (size_t)(t + 1) * kstep;
;       const char* a2 = last ? nA : cA + (size_t)(t + 2) * kstep; const char* b2 = last ? nB : cB + (size_t)(t + 2) * kstep;
;       const char* a3 = a2 + kstep; const char* b3 = b2 + kstep;
;     ...
;     for (int a = 0; a < 2; ++a)
; #pragma unroll
;       for (int b = 0; b < 2; ++b)
; #pragma unroll
;         for (int m = 0; m < 4; ++m)
; #pragma unroll
;           for (int n = 0; n < 2; ++n) acc[a][b][m][n] = (f32x4){0.f, 0.f, 0.f, 0.f};
.LBB0_1276:
	s_ashr_i32 s41, s40, 31
	s_lshl_b64 s[42:43], s[40:41], 20
	v_cmp_lt_i64_e32 vcc, s[44:45], v[174:175]
	s_add_u32 s44, s56, s42
	s_addc_u32 s45, s57, s43
	s_and_b64 s[42:43], vcc, exec
	s_cselect_b32 s41, s45, s15
	s_cselect_b32 s42, s44, s14
	s_ashr_i32 s39, s38, 31
	s_lshl_b64 s[46:47], s[38:39], 20
	s_add_u32 s46, s60, s46
	s_addc_u32 s47, s61, s47
	s_and_b64 s[50:51], vcc, exec
	s_cselect_b32 s39, s47, s49
	s_cselect_b32 s43, s46, s48
	s_add_u32 s14, s14, 0x80080
	s_addc_u32 s15, s15, 0
	s_add_u32 s52, s48, 0x100
	v_mov_b32_e32 v0, 0
	s_addc_u32 s53, s49, 0
	s_mov_b32 s58, -2
	v_mov_b32_e32 v1, v0
	v_mov_b32_e32 v2, v0
	v_mov_b32_e32 v3, v0
	v_mov_b32_e32 v4, v0
	v_mov_b32_e32 v5, v0
	v_mov_b32_e32 v6, v0
	v_mov_b32_e32 v7, v0
	v_mov_b32_e32 v8, v0
	v_mov_b32_e32 v9, v0
	v_mov_b32_e32 v10, v0
	v_mov_b32_e32 v11, v0
	v_mov_b32_e32 v24, v0
	v_mov_b32_e32 v25, v0
	v_mov_b32_e32 v26, v0
	v_mov_b32_e32 v27, v0
	v_mov_b32_e32 v32, v0
	v_mov_b32_e32 v33, v0
	v_mov_b32_e32 v34, v0
	v_mov_b32_e32 v35, v0
	v_mov_b32_e32 v40, v0
	v_mov_b32_e32 v41, v0
	v_mov_b32_e32 v42, v0
	v_mov_b32_e32 v43, v0
	v_mov_b32_e32 v52, v0
	v_mov_b32_e32 v53, v0
	v_mov_b32_e32 v54, v0
	v_mov_b32_e32 v55, v0
	v_mov_b32_e32 v56, v0
	v_mov_b32_e32 v57, v0
	v_mov_b32_e32 v58, v0
	v_mov_b32_e32 v59, v0
	v_mov_b32_e32 v12, v0
	v_mov_b32_e32 v13, v0
	v_mov_b32_e32 v14, v0
	v_mov_b32_e32 v15, v0
	v_mov_b32_e32 v16, v0
	v_mov_b32_e32 v17, v0
	v_mov_b32_e32 v18, v0
	v_mov_b32_e32 v19, v0
	v_mov_b32_e32 v20, v0
	v_mov_b32_e32 v21, v0
	v_mov_b32_e32 v22, v0
	v_mov_b32_e32 v23, v0
	v_mov_b32_e32 v28, v0
	v_mov_b32_e32 v29, v0
	v_mov_b32_e32 v30, v0
	v_mov_b32_e32 v31, v0
	v_mov_b32_e32 v36, v0
	v_mov_b32_e32 v37, v0
	v_mov_b32_e32 v38, v0
	v_mov_b32_e32 v39, v0
	v_mov_b32_e32 v44, v0
	v_mov_b32_e32 v45, v0
	v_mov_b32_e32 v46, v0
	v_mov_b32_e32 v47, v0
	v_mov_b32_e32 v48, v0
	v_mov_b32_e32 v49, v0
	v_mov_b32_e32 v50, v0
	v_mov_b32_e32 v51, v0
	v_mov_b32_e32 v60, v0
	v_mov_b32_e32 v61, v0
	v_mov_b32_e32 v62, v0
	v_mov_b32_e32 v63, v0
	v_mov_b32_e32 v96, v0
	v_mov_b32_e32 v97, v0
	v_mov_b32_e32 v98, v0
	v_mov_b32_e32 v99, v0
	v_mov_b32_e32 v100, v0
	v_mov_b32_e32 v101, v0
	v_mov_b32_e32 v102, v0
	v_mov_b32_e32 v103, v0
	v_mov_b32_e32 v104, v0
	v_mov_b32_e32 v105, v0
	v_mov_b32_e32 v106, v0
	v_mov_b32_e32 v107, v0
	v_mov_b32_e32 v120, v0
	v_mov_b32_e32 v121, v0
	v_mov_b32_e32 v122, v0
	v_mov_b32_e32 v123, v0
	v_mov_b32_e32 v128, v0
	v_mov_b32_e32 v129, v0
	v_mov_b32_e32 v130, v0
	v_mov_b32_e32 v131, v0
	v_mov_b32_e32 v136, v0
	v_mov_b32_e32 v137, v0
	v_mov_b32_e32 v138, v0
	v_mov_b32_e32 v139, v0
	v_mov_b32_e32 v148, v0
	v_mov_b32_e32 v149, v0
	v_mov_b32_e32 v150, v0
	v_mov_b32_e32 v151, v0
	v_mov_b32_e32 v152, v0
	v_mov_b32_e32 v153, v0
	v_mov_b32_e32 v154, v0
	v_mov_b32_e32 v155, v0
	v_mov_b32_e32 v108, v0
	v_mov_b32_e32 v109, v0
	v_mov_b32_e32 v110, v0
	v_mov_b32_e32 v111, v0
	v_mov_b32_e32 v112, v0
	v_mov_b32_e32 v113, v0
	v_mov_b32_e32 v114, v0
	v_mov_b32_e32 v115, v0
	v_mov_b32_e32 v116, v0
	v_mov_b32_e32 v117, v0
	v_mov_b32_e32 v118, v0
	v_mov_b32_e32 v119, v0
	v_mov_b32_e32 v124, v0
	v_mov_b32_e32 v125, v0
	v_mov_b32_e32 v126, v0
	v_mov_b32_e32 v127, v0
	v_mov_b32_e32 v132, v0
	v_mov_b32_e32 v133, v0
	v_mov_b32_e32 v134, v0
	v_mov_b32_e32 v135, v0
	v_mov_b32_e32 v140, v0
	v_mov_b32_e32 v141, v0
	v_mov_b32_e32 v142, v0
	v_mov_b32_e32 v143, v0
	v_mov_b32_e32 v144, v0
	v_mov_b32_e32 v145, v0
	v_mov_b32_e32 v146, v0
	v_mov_b32_e32 v147, v0
	v_mov_b32_e32 v156, v0
	v_mov_b32_e32 v157, v0
	v_mov_b32_e32 v158, v0
	v_mov_b32_e32 v159, v0
	.p2align	6

; template <class Epi, class Sched = StaticOrder>
; DI void gemm_phase(LAS unsigned char* lds, const Gemm g, const Sched& S, const Epi& E) {
;     ...
;     for (int t = 0; t < nt; t += 2) {
;       const bool last = (t == nt - 2);
;       const char* a1 = cA + (size_t)(t + 1) * kstep;
;       const char* a2 = last ? nA : cA + (size_t)(t + 2) * kstep; const char* b2 = last ? nB : cB + (size_t)(t + 2) * kstep;
;       const char* a3 = a2 + kstep; const char* b3 = b2 + kstep;
;     ...
;     for (int a = 0; a < 2; ++a)
; #pragma unroll
;       for (int b = 0; b < 2; ++b)
; #pragma unroll
;         for (int m = 0; m < 4; ++m)
; #pragma unroll
;           for (int n = 0; n < 2; ++n) acc[a][b][m][n] = (f32x4){0.f, 0.f, 0.f, 0.f};
.LBB0_1423:
	s_add_u32 s16, s16, 0x160080
	s_addc_u32 s17, s17, 0
	s_add_u32 s45, s18, 0x100
	v_mov_b32_e32 v0, 0
	s_addc_u32 s46, s19, 0
	s_mov_b32 s47, -2
	v_mov_b32_e32 v1, v0
	v_mov_b32_e32 v2, v0
	v_mov_b32_e32 v3, v0
	v_mov_b32_e32 v4, v0
	v_mov_b32_e32 v5, v0
	v_mov_b32_e32 v6, v0
	v_mov_b32_e32 v7, v0
	v_mov_b32_e32 v8, v0
	v_mov_b32_e32 v9, v0
	v_mov_b32_e32 v10, v0
	v_mov_b32_e32 v11, v0
	v_mov_b32_e32 v16, v0
	v_mov_b32_e32 v17, v0
	v_mov_b32_e32 v18, v0
	v_mov_b32_e32 v19, v0
	v_mov_b32_e32 v24, v0
	v_mov_b32_e32 v25, v0
	v_mov_b32_e32 v26, v0
	v_mov_b32_e32 v27, v0
	v_mov_b32_e32 v32, v0
	v_mov_b32_e32 v33, v0
	v_mov_b32_e32 v34, v0
	v_mov_b32_e32 v35, v0
	v_mov_b32_e32 v40, v0
	v_mov_b32_e32 v41, v0
	v_mov_b32_e32 v42, v0
	v_mov_b32_e32 v43, v0
	v_mov_b32_e32 v48, v0
	v_mov_b32_e32 v49, v0
	v_mov_b32_e32 v50, v0
	v_mov_b32_e32 v51, v0
	v_mov_b32_e32 v12, v0
	v_mov_b32_e32 v13, v0
	v_mov_b32_e32 v14, v0
	v_mov_b32_e32 v15, v0
	v_mov_b32_e32 v20, v0
	v_mov_b32_e32 v21, v0
	v_mov_b32_e32 v22, v0
	v_mov_b32_e32 v23, v0
	v_mov_b32_e32 v28, v0
	v_mov_b32_e32 v29, v0
	v_mov_b32_e32 v30, v0
	v_mov_b32_e32 v31, v0
	v_mov_b32_e32 v36, v0
	v_mov_b32_e32 v37, v0
	v_mov_b32_e32 v38, v0
	v_mov_b32_e32 v39, v0
	v_mov_b32_e32 v44, v0
	v_mov_b32_e32 v45, v0
	v_mov_b32_e32 v46, v0
	v_mov_b32_e32 v47, v0
	v_mov_b32_e32 v52, v0
	v_mov_b32_e32 v53, v0
	v_mov_b32_e32 v54, v0
	v_mov_b32_e32 v55, v0
	v_mov_b32_e32 v56, v0
	v_mov_b32_e32 v57, v0
	v_mov_b32_e32 v58, v0
	v_mov_b32_e32 v59, v0
	v_mov_b32_e32 v60, v0
	v_mov_b32_e32 v61, v0
	v_mov_b32_e32 v62, v0
	v_mov_b32_e32 v63, v0
	v_mov_b32_e32 v64, v0
	v_mov_b32_e32 v65, v0
	v_mov_b32_e32 v66, v0
	v_mov_b32_e32 v67, v0
	v_mov_b32_e32 v68, v0
	v_mov_b32_e32 v69, v0
	v_mov_b32_e32 v70, v0
	v_mov_b32_e32 v71, v0
	v_mov_b32_e32 v72, v0
	v_mov_b32_e32 v73, v0
	v_mov_b32_e32 v74, v0
	v_mov_b32_e32 v75, v0
	v_mov_b32_e32 v76, v0
	v_mov_b32_e32 v77, v0
	v_mov_b32_e32 v78, v0
	v_mov_b32_e32 v79, v0
	v_mov_b32_e32 v84, v0
	v_mov_b32_e32 v85, v0
	v_mov_b32_e32 v86, v0
	v_mov_b32_e32 v87, v0
	v_mov_b32_e32 v92, v0
	v_mov_b32_e32 v93, v0
	v_mov_b32_e32 v94, v0
	v_mov_b32_e32 v95, v0
	v_mov_b32_e32 v100, v0
	v_mov_b32_e32 v101, v0
	v_mov_b32_e32 v102, v0
	v_mov_b32_e32 v103, v0
	v_mov_b32_e32 v108, v0
	v_mov_b32_e32 v109, v0
	v_mov_b32_e32 v110, v0
	v_mov_b32_e32 v111, v0
	v_mov_b32_e32 v80, v0
	v_mov_b32_e32 v81, v0
	v_mov_b32_e32 v82, v0
	v_mov_b32_e32 v83, v0
	v_mov_b32_e32 v88, v0
	v_mov_b32_e32 v89, v0
	v_mov_b32_e32 v90, v0
	v_mov_b32_e32 v91, v0
	v_mov_b32_e32 v96, v0
	v_mov_b32_e32 v97, v0
	v_mov_b32_e32 v98, v0
	v_mov_b32_e32 v99, v0
	v_mov_b32_e32 v104, v0
	v_mov_b32_e32 v105, v0
	v_mov_b32_e32 v106, v0
	v_mov_b32_e32 v107, v0
	v_mov_b32_e32 v112, v0
	v_mov_b32_e32 v113, v0
	v_mov_b32_e32 v114, v0
	v_mov_b32_e32 v115, v0
	v_mov_b32_e32 v116, v0
	v_mov_b32_e32 v117, v0
	v_mov_b32_e32 v118, v0
	v_mov_b32_e32 v119, v0
	v_mov_b32_e32 v120, v0
	v_mov_b32_e32 v121, v0
	v_mov_b32_e32 v122, v0
	v_mov_b32_e32 v123, v0
	v_mov_b32_e32 v124, v0
	v_mov_b32_e32 v125, v0
	v_mov_b32_e32 v126, v0
	v_mov_b32_e32 v127, v0
	.p2align	6
